# FFN-in: per-row SSQ sums computed once per tile during the peeled first K iteration and cached in spare LDS; epilogue reads them with ds_read_b32 (8 global loads and the cross-lane reduction network r
# speedup vs baseline: 1.0137x; 1.0137x over previous
.LBB0_556:
	v_mov_b64_e32 v[0:1], 0x420
	s_ashr_i32 s49, s48, 31
	v_cmp_lt_i64_e32 vcc, s[50:51], v[0:1]
	s_lshl_b64 s[50:51], s[48:49], 19
	s_add_u32 s50, s4, s50
	s_addc_u32 s51, s5, s51
	s_and_b64 s[52:53], vcc, exec
	s_cselect_b32 s49, s51, s59
	s_cselect_b32 s67, s50, s58
	s_ashr_i32 s47, s46, 31
	s_lshl_b64 s[52:53], s[46:47], 19
	s_add_u32 s52, s10, s52
	s_addc_u32 s53, s11, s53
	s_and_b64 s[62:63], vcc, exec
	s_cselect_b32 s47, s53, s61
	s_cselect_b32 s68, s52, s60
	s_add_u32 s58, s58, 0x40080
	s_addc_u32 s59, s59, 0
	s_add_u32 s69, s60, 0x100
	s_addc_u32 s70, s61, 0
	s_mov_b32 s71, -2
	v_add_u32_e32 v96, 0x10000, v193
	ds_read_b128 v[80:83], v96
	ds_read_b128 v[88:91], v96 offset:1024
	ds_read_b128 v[102:105], v96 offset:2048
	ds_read_b128 v[106:109], v96 offset:3072
	s_add_u32 s60, s58, 0xfffc0080
	s_addc_u32 s61, s59, -1
	s_add_i32 s72, 0, 0x10000
	v_add_u32_e32 v96, s72, v193
	s_cmp_eq_u32 s71, 12
	s_cselect_b32 s63, s49, s61
	s_cselect_b32 s62, s67, s60
	s_cselect_b32 s61, s47, s70
	s_cselect_b32 s60, s68, s69
	s_lshl_b32 s100, s54, 8
	s_lshr_b32 s101, s18, 5
	s_add_i32 s100, s100, s101
	v_add_u32_e32 v244, s100, v192
	v_lshlrev_b32_e32 v244, 6, v244
	v_mov_b32_e32 v245, 0
	v_lshl_add_u64 v[244:245], v[154:155], 0, v[244:245]
	global_load_dwordx4 v[248:251], v[244:245], off
	global_load_dwordx4 v[244:247], v[244:245], off offset:1024
	s_add_i32 m0, s27, 0xc000
	ds_read_b128 v[160:163], v195
	ds_read_b128 v[164:167], v195 offset:1024
	ds_read_b128 v[168:171], v195 offset:2048
	ds_read_b128 v[172:175], v195 offset:3072
	ds_read_b128 v[182:185], v195 offset:4096
	ds_read_b128 v[186:189], v195 offset:5120
	ds_read_b128 v[196:199], v195 offset:6144
	ds_read_b128 v[200:203], v195 offset:7168
	global_load_lds_dwordx4 v156, s[58:59]
	s_add_i32 m0, s27, 0xe000
	s_nop 0
	global_load_lds_dwordx4 v158, s[58:59]
	s_setprio 1
	s_barrier
	s_waitcnt lgkmcnt(0)
	v_mfma_f32_16x16x32_bf16 v[142:145], v[80:83], v[160:163], 0
	v_mfma_f32_16x16x32_bf16 v[138:141], v[102:105], v[160:163], 0
	v_mfma_f32_16x16x32_bf16 v[126:129], v[80:83], v[168:171], 0
	v_mfma_f32_16x16x32_bf16 v[122:125], v[102:105], v[168:171], 0
	v_mfma_f32_16x16x32_bf16 v[110:113], v[80:83], v[182:185], 0
	v_mfma_f32_16x16x32_bf16 v[98:101], v[102:105], v[182:185], 0
	v_mfma_f32_16x16x32_bf16 v[76:79], v[80:83], v[196:199], 0
	v_mfma_f32_16x16x32_bf16 v[72:75], v[102:105], v[196:199], 0
	v_mfma_f32_16x16x32_bf16 v[142:145], v[88:91], v[164:167], v[142:145]
	v_mfma_f32_16x16x32_bf16 v[138:141], v[106:109], v[164:167], v[138:141]
	v_mfma_f32_16x16x32_bf16 v[126:129], v[88:91], v[172:175], v[126:129]
	v_mfma_f32_16x16x32_bf16 v[122:125], v[106:109], v[172:175], v[122:125]
	v_mfma_f32_16x16x32_bf16 v[110:113], v[88:91], v[186:189], v[110:113]
	v_mfma_f32_16x16x32_bf16 v[98:101], v[106:109], v[186:189], v[98:101]
	v_mfma_f32_16x16x32_bf16 v[76:79], v[88:91], v[200:203], v[76:79]
	v_mfma_f32_16x16x32_bf16 v[72:75], v[106:109], v[200:203], v[72:75]
	s_barrier
	s_setprio 0
	s_add_i32 s76, 0, 0x14000
	s_add_i32 s72, s72, s18
	v_add_u32_e32 v96, s76, v193
	v_lshl_add_u64 v[176:177], s[60:61], 0, v[150:151]
	s_mov_b32 m0, s72
	ds_read_b128 v[224:227], v96
	ds_read_b128 v[228:231], v96 offset:1024
	ds_read_b128 v[232:235], v96 offset:2048
	ds_read_b128 v[236:239], v96 offset:3072
	global_load_lds_dwordx4 v150, s[60:61]
	v_lshl_add_u64 v[190:191], s[60:61], 0, v[146:147]
	s_add_i32 m0, s72, 0x2000
	s_nop 0
	global_load_lds_dwordx4 v146, s[60:61]
	s_setprio 1
	s_barrier
	s_waitcnt lgkmcnt(0)
	v_mfma_f32_16x16x32_bf16 v[134:137], v[224:227], v[160:163], 0
	v_mfma_f32_16x16x32_bf16 v[130:133], v[232:235], v[160:163], 0
	v_mfma_f32_16x16x32_bf16 v[118:121], v[224:227], v[168:171], 0
	s_mov_b32 m0, s27
	v_mfma_f32_16x16x32_bf16 v[114:117], v[232:235], v[168:171], 0
	v_lshl_add_u64 v[240:241], s[62:63], 0, v[152:153]
	v_mfma_f32_16x16x32_bf16 v[92:95], v[224:227], v[182:185], 0
	v_mfma_f32_16x16x32_bf16 v[84:87], v[232:235], v[182:185], 0
	v_mfma_f32_16x16x32_bf16 v[68:71], v[224:227], v[196:199], 0
	v_mfma_f32_16x16x32_bf16 v[64:67], v[232:235], v[196:199], 0
	v_mfma_f32_16x16x32_bf16 v[134:137], v[228:231], v[164:167], v[134:137]
	v_mfma_f32_16x16x32_bf16 v[130:133], v[236:239], v[164:167], v[130:133]
	v_mfma_f32_16x16x32_bf16 v[118:121], v[228:231], v[172:175], v[118:121]
	v_mfma_f32_16x16x32_bf16 v[114:117], v[236:239], v[172:175], v[114:117]
	v_mfma_f32_16x16x32_bf16 v[92:95], v[228:231], v[186:189], v[92:95]
	v_mfma_f32_16x16x32_bf16 v[84:87], v[236:239], v[186:189], v[84:87]
	v_mfma_f32_16x16x32_bf16 v[68:71], v[228:231], v[200:203], v[68:71]
	v_mfma_f32_16x16x32_bf16 v[64:67], v[236:239], v[200:203], v[64:67]
	s_barrier
	s_setprio 0
	ds_read_b128 v[160:163], v195 offset:16384
	ds_read_b128 v[164:167], v195 offset:17408
	ds_read_b128 v[168:171], v195 offset:18432
	ds_read_b128 v[172:175], v195 offset:19456
	ds_read_b128 v[182:185], v195 offset:20480
	ds_read_b128 v[186:189], v195 offset:21504
	ds_read_b128 v[196:199], v195 offset:22528
	ds_read_b128 v[200:203], v195 offset:23552
	global_load_lds_dwordx4 v152, s[62:63]
	v_lshl_add_u64 v[242:243], s[62:63], 0, v[148:149]
	s_mov_b32 m0, s28
	s_nop 0
	global_load_lds_dwordx4 v148, s[62:63]
	s_waitcnt vmcnt(12)
	s_setprio 1
	s_barrier
	s_waitcnt lgkmcnt(0)
	v_mfma_f32_16x16x32_bf16 v[60:63], v[80:83], v[160:163], 0
	v_mfma_f32_16x16x32_bf16 v[56:59], v[102:105], v[160:163], 0
	v_mfma_f32_16x16x32_bf16 v[44:47], v[80:83], v[168:171], 0
	v_mfma_f32_16x16x32_bf16 v[40:43], v[102:105], v[168:171], 0
	v_mfma_f32_16x16x32_bf16 v[28:31], v[80:83], v[182:185], 0
	v_mfma_f32_16x16x32_bf16 v[24:27], v[102:105], v[182:185], 0
	v_mfma_f32_16x16x32_bf16 v[12:15], v[80:83], v[196:199], 0
	v_mfma_f32_16x16x32_bf16 v[8:11], v[102:105], v[196:199], 0
	v_mfma_f32_16x16x32_bf16 v[60:63], v[88:91], v[164:167], v[60:63]
	v_mfma_f32_16x16x32_bf16 v[56:59], v[106:109], v[164:167], v[56:59]
	v_mfma_f32_16x16x32_bf16 v[44:47], v[88:91], v[172:175], v[44:47]
	v_mfma_f32_16x16x32_bf16 v[40:43], v[106:109], v[172:175], v[40:43]
	v_mfma_f32_16x16x32_bf16 v[28:31], v[88:91], v[186:189], v[28:31]
	v_mfma_f32_16x16x32_bf16 v[24:27], v[106:109], v[186:189], v[24:27]
	v_mfma_f32_16x16x32_bf16 v[12:15], v[88:91], v[200:203], v[12:15]
	v_mfma_f32_16x16x32_bf16 v[8:11], v[106:109], v[200:203], v[8:11]
	s_barrier
	s_setprio 0
	v_add_u32_e32 v96, 0x18000, v193
	ds_read_b128 v[80:83], v96
	ds_read_b128 v[88:91], v96 offset:1024
	ds_read_b128 v[102:105], v96 offset:2048
	ds_read_b128 v[106:109], v96 offset:3072
	s_add_u32 s74, s60, 0x40000
	s_addc_u32 s75, s61, 0
	s_add_i32 s72, s76, s18
	s_mov_b32 m0, s72
	s_nop 0
	global_load_lds_dwordx4 v150, s[74:75]
	s_add_i32 m0, s72, 0x2000
	s_nop 0
	global_load_lds_dwordx4 v146, s[74:75]
	s_waitcnt vmcnt(6)
	s_setprio 1
	s_barrier
	v_mfma_f32_16x16x32_bf16 v[52:55], v[224:227], v[160:163], 0
	v_add_f32_e32 v248, v248, v249
	v_add_f32_e32 v250, v250, v251
	v_add_f32_e32 v248, v248, v250
	v_add_f32_e32 v244, v244, v245
	v_add_f32_e32 v246, v246, v247
	v_add_f32_e32 v244, v244, v246
	v_mov_b32_e32 v249, v248
	v_mov_b32_e32 v245, v244
	s_nop 1
	v_permlane16_swap_b32_e32 v248, v249
	v_permlane16_swap_b32_e32 v244, v245
	s_nop 1
	v_add_f32_e32 v248, v248, v249
	v_add_f32_e32 v244, v244, v245
	v_mov_b32_e32 v249, v248
	v_mov_b32_e32 v245, v244
	s_nop 1
	v_permlane32_swap_b32_e32 v248, v249
	v_permlane32_swap_b32_e32 v244, v245
	s_nop 1
	v_add_f32_e32 v248, v248, v249
	v_add_f32_e32 v244, v244, v245
	v_mul_f32_e32 v248, 0.5, v248
	v_mul_f32_e32 v244, 0.5, v244
	s_lshr_b32 s101, s18, 3
	s_add_i32 s101, s101, 0x20000
	v_lshl_add_u32 v250, v192, 2, s101
	ds_write_b32 v250, v248
	ds_write_b32 v250, v244 offset:64
	v_mfma_f32_16x16x32_bf16 v[48:51], v[232:235], v[160:163], 0
	v_mfma_f32_16x16x32_bf16 v[36:39], v[224:227], v[168:171], 0
	s_add_i32 s72, 0, 0x18000
	v_mfma_f32_16x16x32_bf16 v[32:35], v[232:235], v[168:171], 0
	v_add_u32_e32 v96, s72, v193
	v_mfma_f32_16x16x32_bf16 v[20:23], v[224:227], v[182:185], 0
	v_mfma_f32_16x16x32_bf16 v[16:19], v[232:235], v[182:185], 0
	v_mfma_f32_16x16x32_bf16 v[4:7], v[224:227], v[196:199], 0
	v_mfma_f32_16x16x32_bf16 v[0:3], v[232:235], v[196:199], 0
	v_mfma_f32_16x16x32_bf16 v[52:55], v[228:231], v[164:167], v[52:55]
	v_mfma_f32_16x16x32_bf16 v[48:51], v[236:239], v[164:167], v[48:51]
	v_mfma_f32_16x16x32_bf16 v[36:39], v[228:231], v[172:175], v[36:39]
	v_mfma_f32_16x16x32_bf16 v[32:35], v[236:239], v[172:175], v[32:35]
	v_mfma_f32_16x16x32_bf16 v[20:23], v[228:231], v[186:189], v[20:23]
	v_mfma_f32_16x16x32_bf16 v[16:19], v[236:239], v[186:189], v[16:19]
	v_mfma_f32_16x16x32_bf16 v[4:7], v[228:231], v[200:203], v[4:7]
	v_mfma_f32_16x16x32_bf16 v[0:3], v[236:239], v[200:203], v[0:3]
	s_barrier
	s_setprio 0
	s_add_u32 s62, s62, 0x40000
	s_addc_u32 s63, s63, 0
	s_mov_b32 m0, s37
	ds_read_b128 v[160:163], v195 offset:32768
	ds_read_b128 v[164:167], v195 offset:33792
	ds_read_b128 v[168:171], v195 offset:34816
	ds_read_b128 v[172:175], v195 offset:35840
	ds_read_b128 v[182:185], v195 offset:36864
	ds_read_b128 v[186:189], v195 offset:37888
	ds_read_b128 v[196:199], v195 offset:38912
	ds_read_b128 v[200:203], v195 offset:39936
	global_load_lds_dwordx4 v152, s[62:63]
	s_mov_b32 m0, s56
	s_nop 0
	global_load_lds_dwordx4 v148, s[62:63]
	s_setprio 1
	s_barrier
	s_waitcnt lgkmcnt(0)
	v_mfma_f32_16x16x32_bf16 v[142:145], v[80:83], v[160:163], v[142:145]
	v_mfma_f32_16x16x32_bf16 v[138:141], v[102:105], v[160:163], v[138:141]
	v_mfma_f32_16x16x32_bf16 v[126:129], v[80:83], v[168:171], v[126:129]
	v_mfma_f32_16x16x32_bf16 v[122:125], v[102:105], v[168:171], v[122:125]
	v_mfma_f32_16x16x32_bf16 v[110:113], v[80:83], v[182:185], v[110:113]
	v_mfma_f32_16x16x32_bf16 v[98:101], v[102:105], v[182:185], v[98:101]
	v_mfma_f32_16x16x32_bf16 v[76:79], v[80:83], v[196:199], v[76:79]
	v_mfma_f32_16x16x32_bf16 v[72:75], v[102:105], v[196:199], v[72:75]
	v_mfma_f32_16x16x32_bf16 v[142:145], v[88:91], v[164:167], v[142:145]
	v_mfma_f32_16x16x32_bf16 v[138:141], v[106:109], v[164:167], v[138:141]
	v_mfma_f32_16x16x32_bf16 v[126:129], v[88:91], v[172:175], v[126:129]
	v_mfma_f32_16x16x32_bf16 v[122:125], v[106:109], v[172:175], v[122:125]
	v_mfma_f32_16x16x32_bf16 v[110:113], v[88:91], v[186:189], v[110:113]
	v_mfma_f32_16x16x32_bf16 v[98:101], v[106:109], v[186:189], v[98:101]
	v_mfma_f32_16x16x32_bf16 v[76:79], v[88:91], v[200:203], v[76:79]
	v_mfma_f32_16x16x32_bf16 v[72:75], v[106:109], v[200:203], v[72:75]
	s_barrier
	s_setprio 0
	s_add_i32 s62, 0, 0x1c000
	s_add_i32 s63, s72, s18
	v_add_u32_e32 v96, s62, v193
	v_lshl_add_u64 v[176:177], v[176:177], 0, s[6:7]
	s_mov_b32 m0, s63
	ds_read_b128 v[224:227], v96
	ds_read_b128 v[228:231], v96 offset:1024
	ds_read_b128 v[232:235], v96 offset:2048
	ds_read_b128 v[236:239], v96 offset:3072
	global_load_lds_dwordx4 v[176:177], off
	v_lshl_add_u64 v[176:177], v[190:191], 0, s[6:7]
	s_add_i32 m0, s63, 0x2000
	s_nop 0
	global_load_lds_dwordx4 v[176:177], off
	s_setprio 1
	s_barrier
	s_waitcnt lgkmcnt(0)
	v_mfma_f32_16x16x32_bf16 v[134:137], v[224:227], v[160:163], v[134:137]
	v_mfma_f32_16x16x32_bf16 v[130:133], v[232:235], v[160:163], v[130:133]
	v_mfma_f32_16x16x32_bf16 v[118:121], v[224:227], v[168:171], v[118:121]
	s_mov_b32 m0, s64
	v_mfma_f32_16x16x32_bf16 v[114:117], v[232:235], v[168:171], v[114:117]
	v_lshl_add_u64 v[176:177], v[240:241], 0, s[6:7]
	v_mfma_f32_16x16x32_bf16 v[92:95], v[224:227], v[182:185], v[92:95]
	v_mfma_f32_16x16x32_bf16 v[84:87], v[232:235], v[182:185], v[84:87]
	v_mfma_f32_16x16x32_bf16 v[68:71], v[224:227], v[196:199], v[68:71]
	v_mfma_f32_16x16x32_bf16 v[64:67], v[232:235], v[196:199], v[64:67]
	v_mfma_f32_16x16x32_bf16 v[134:137], v[228:231], v[164:167], v[134:137]
	v_mfma_f32_16x16x32_bf16 v[130:133], v[236:239], v[164:167], v[130:133]
	v_mfma_f32_16x16x32_bf16 v[118:121], v[228:231], v[172:175], v[118:121]
	v_mfma_f32_16x16x32_bf16 v[114:117], v[236:239], v[172:175], v[114:117]
	v_mfma_f32_16x16x32_bf16 v[92:95], v[228:231], v[186:189], v[92:95]
	v_mfma_f32_16x16x32_bf16 v[84:87], v[236:239], v[186:189], v[84:87]
	v_mfma_f32_16x16x32_bf16 v[68:71], v[228:231], v[200:203], v[68:71]
	v_mfma_f32_16x16x32_bf16 v[64:67], v[236:239], v[200:203], v[64:67]
	s_barrier
	s_setprio 0
	ds_read_b128 v[160:163], v195 offset:49152
	ds_read_b128 v[164:167], v195 offset:50176
	ds_read_b128 v[168:171], v195 offset:51200
	ds_read_b128 v[172:175], v195 offset:52224
	ds_read_b128 v[182:185], v195 offset:53248
	ds_read_b128 v[186:189], v195 offset:54272
	ds_read_b128 v[196:199], v195 offset:55296
	ds_read_b128 v[200:203], v195 offset:56320
	global_load_lds_dwordx4 v[176:177], off
	v_lshl_add_u64 v[176:177], v[242:243], 0, s[6:7]
	s_mov_b32 m0, s65
	s_nop 0
	global_load_lds_dwordx4 v[176:177], off
	s_waitcnt vmcnt(10)
	s_setprio 1
	s_barrier
	s_waitcnt lgkmcnt(0)
	v_mfma_f32_16x16x32_bf16 v[60:63], v[80:83], v[160:163], v[60:63]
	v_mfma_f32_16x16x32_bf16 v[56:59], v[102:105], v[160:163], v[56:59]
	v_mfma_f32_16x16x32_bf16 v[44:47], v[80:83], v[168:171], v[44:47]
	v_mfma_f32_16x16x32_bf16 v[40:43], v[102:105], v[168:171], v[40:43]
	v_mfma_f32_16x16x32_bf16 v[28:31], v[80:83], v[182:185], v[28:31]
	v_mfma_f32_16x16x32_bf16 v[24:27], v[102:105], v[182:185], v[24:27]
	v_mfma_f32_16x16x32_bf16 v[12:15], v[80:83], v[196:199], v[12:15]
	v_mfma_f32_16x16x32_bf16 v[8:11], v[102:105], v[196:199], v[8:11]
	v_mfma_f32_16x16x32_bf16 v[60:63], v[88:91], v[164:167], v[60:63]
	v_mfma_f32_16x16x32_bf16 v[56:59], v[106:109], v[164:167], v[56:59]
	v_mfma_f32_16x16x32_bf16 v[44:47], v[88:91], v[172:175], v[44:47]
	v_mfma_f32_16x16x32_bf16 v[40:43], v[106:109], v[172:175], v[40:43]
	v_mfma_f32_16x16x32_bf16 v[28:31], v[88:91], v[186:189], v[28:31]
	v_mfma_f32_16x16x32_bf16 v[24:27], v[106:109], v[186:189], v[24:27]
	v_mfma_f32_16x16x32_bf16 v[12:15], v[88:91], v[200:203], v[12:15]
	v_mfma_f32_16x16x32_bf16 v[8:11], v[106:109], v[200:203], v[8:11]
	s_barrier
	s_setprio 0
	v_add_u32_e32 v96, 0x10000, v193
	ds_read_b128 v[80:83], v96
	ds_read_b128 v[88:91], v96 offset:1024
	ds_read_b128 v[102:105], v96 offset:2048
	ds_read_b128 v[106:109], v96 offset:3072
	s_add_u32 s60, s60, 0x40080
	s_addc_u32 s61, s61, 0
	s_add_i32 s62, s62, s18
	s_mov_b32 m0, s62
	s_nop 0
	global_load_lds_dwordx4 v150, s[60:61]
	s_add_i32 m0, s62, 0x2000
	s_nop 0
	global_load_lds_dwordx4 v146, s[60:61]
	s_waitcnt vmcnt(6)
	s_setprio 1
	s_barrier
	v_mfma_f32_16x16x32_bf16 v[52:55], v[224:227], v[160:163], v[52:55]
	v_mfma_f32_16x16x32_bf16 v[48:51], v[232:235], v[160:163], v[48:51]
	v_mfma_f32_16x16x32_bf16 v[36:39], v[224:227], v[168:171], v[36:39]
	s_add_i32 s71, s71, 2
	v_mfma_f32_16x16x32_bf16 v[32:35], v[232:235], v[168:171], v[32:35]
	s_add_u32 s58, s58, 0x100
	v_mfma_f32_16x16x32_bf16 v[20:23], v[224:227], v[182:185], v[20:23]
	s_addc_u32 s59, s59, 0
	v_mfma_f32_16x16x32_bf16 v[16:19], v[232:235], v[182:185], v[16:19]
	s_add_u32 s69, s69, 0x100
	v_mfma_f32_16x16x32_bf16 v[4:7], v[224:227], v[196:199], v[4:7]
	s_addc_u32 s70, s70, 0
	v_mfma_f32_16x16x32_bf16 v[0:3], v[232:235], v[196:199], v[0:3]
	s_cmp_gt_u32 s71, 13
	v_mfma_f32_16x16x32_bf16 v[52:55], v[228:231], v[164:167], v[52:55]
	v_mfma_f32_16x16x32_bf16 v[48:51], v[236:239], v[164:167], v[48:51]
	v_mfma_f32_16x16x32_bf16 v[36:39], v[228:231], v[172:175], v[36:39]
	v_mfma_f32_16x16x32_bf16 v[32:35], v[236:239], v[172:175], v[32:35]
	v_mfma_f32_16x16x32_bf16 v[20:23], v[228:231], v[186:189], v[20:23]
	v_mfma_f32_16x16x32_bf16 v[16:19], v[236:239], v[186:189], v[16:19]
	v_mfma_f32_16x16x32_bf16 v[4:7], v[228:231], v[200:203], v[4:7]
	v_mfma_f32_16x16x32_bf16 v[0:3], v[236:239], v[200:203], v[0:3]
	s_barrier
	s_setprio 0
.LBB0_557:
	s_add_u32 s60, s58, 0xfffc0080
	s_addc_u32 s61, s59, -1
	s_add_i32 s72, 0, 0x10000
	v_add_u32_e32 v96, s72, v193
	s_cmp_eq_u32 s71, 12
	s_cselect_b32 s63, s49, s61
	s_cselect_b32 s62, s67, s60
	s_cselect_b32 s61, s47, s70
	s_cselect_b32 s60, s68, s69
	s_add_i32 m0, s27, 0xc000
	ds_read_b128 v[160:163], v195
	ds_read_b128 v[164:167], v195 offset:1024
	ds_read_b128 v[168:171], v195 offset:2048
	ds_read_b128 v[172:175], v195 offset:3072
	ds_read_b128 v[182:185], v195 offset:4096
	ds_read_b128 v[186:189], v195 offset:5120
	ds_read_b128 v[196:199], v195 offset:6144
	ds_read_b128 v[200:203], v195 offset:7168
	global_load_lds_dwordx4 v156, s[58:59]
	s_add_i32 m0, s27, 0xe000
	s_nop 0
	global_load_lds_dwordx4 v158, s[58:59]
	s_setprio 1
	s_barrier
	s_waitcnt lgkmcnt(0)
	v_mfma_f32_16x16x32_bf16 v[142:145], v[80:83], v[160:163], v[142:145]
	v_mfma_f32_16x16x32_bf16 v[138:141], v[102:105], v[160:163], v[138:141]
	v_mfma_f32_16x16x32_bf16 v[126:129], v[80:83], v[168:171], v[126:129]
	v_mfma_f32_16x16x32_bf16 v[122:125], v[102:105], v[168:171], v[122:125]
	v_mfma_f32_16x16x32_bf16 v[110:113], v[80:83], v[182:185], v[110:113]
	v_mfma_f32_16x16x32_bf16 v[98:101], v[102:105], v[182:185], v[98:101]
	v_mfma_f32_16x16x32_bf16 v[76:79], v[80:83], v[196:199], v[76:79]
	v_mfma_f32_16x16x32_bf16 v[72:75], v[102:105], v[196:199], v[72:75]
	v_mfma_f32_16x16x32_bf16 v[142:145], v[88:91], v[164:167], v[142:145]
	v_mfma_f32_16x16x32_bf16 v[138:141], v[106:109], v[164:167], v[138:141]
	v_mfma_f32_16x16x32_bf16 v[126:129], v[88:91], v[172:175], v[126:129]
	v_mfma_f32_16x16x32_bf16 v[122:125], v[106:109], v[172:175], v[122:125]
	v_mfma_f32_16x16x32_bf16 v[110:113], v[88:91], v[186:189], v[110:113]
	v_mfma_f32_16x16x32_bf16 v[98:101], v[106:109], v[186:189], v[98:101]
	v_mfma_f32_16x16x32_bf16 v[76:79], v[88:91], v[200:203], v[76:79]
	v_mfma_f32_16x16x32_bf16 v[72:75], v[106:109], v[200:203], v[72:75]
	s_barrier
	s_setprio 0
	s_add_i32 s76, 0, 0x14000
	s_add_i32 s72, s72, s18
	v_add_u32_e32 v96, s76, v193
	v_lshl_add_u64 v[176:177], s[60:61], 0, v[150:151]
	s_mov_b32 m0, s72
	ds_read_b128 v[224:227], v96
	ds_read_b128 v[228:231], v96 offset:1024
	ds_read_b128 v[232:235], v96 offset:2048
	ds_read_b128 v[236:239], v96 offset:3072
	global_load_lds_dwordx4 v150, s[60:61]
	v_lshl_add_u64 v[190:191], s[60:61], 0, v[146:147]
	s_add_i32 m0, s72, 0x2000
	s_nop 0
	global_load_lds_dwordx4 v146, s[60:61]
	s_setprio 1
	s_barrier
	s_waitcnt lgkmcnt(0)
	v_mfma_f32_16x16x32_bf16 v[134:137], v[224:227], v[160:163], v[134:137]
	v_mfma_f32_16x16x32_bf16 v[130:133], v[232:235], v[160:163], v[130:133]
	v_mfma_f32_16x16x32_bf16 v[118:121], v[224:227], v[168:171], v[118:121]
	s_mov_b32 m0, s27
	v_mfma_f32_16x16x32_bf16 v[114:117], v[232:235], v[168:171], v[114:117]
	v_lshl_add_u64 v[240:241], s[62:63], 0, v[152:153]
	v_mfma_f32_16x16x32_bf16 v[92:95], v[224:227], v[182:185], v[92:95]
	v_mfma_f32_16x16x32_bf16 v[84:87], v[232:235], v[182:185], v[84:87]
	v_mfma_f32_16x16x32_bf16 v[68:71], v[224:227], v[196:199], v[68:71]
	v_mfma_f32_16x16x32_bf16 v[64:67], v[232:235], v[196:199], v[64:67]
	v_mfma_f32_16x16x32_bf16 v[134:137], v[228:231], v[164:167], v[134:137]
	v_mfma_f32_16x16x32_bf16 v[130:133], v[236:239], v[164:167], v[130:133]
	v_mfma_f32_16x16x32_bf16 v[118:121], v[228:231], v[172:175], v[118:121]
	v_mfma_f32_16x16x32_bf16 v[114:117], v[236:239], v[172:175], v[114:117]
	v_mfma_f32_16x16x32_bf16 v[92:95], v[228:231], v[186:189], v[92:95]
	v_mfma_f32_16x16x32_bf16 v[84:87], v[236:239], v[186:189], v[84:87]
	v_mfma_f32_16x16x32_bf16 v[68:71], v[228:231], v[200:203], v[68:71]
	v_mfma_f32_16x16x32_bf16 v[64:67], v[236:239], v[200:203], v[64:67]
	s_barrier
	s_setprio 0
	ds_read_b128 v[160:163], v195 offset:16384
	ds_read_b128 v[164:167], v195 offset:17408
	ds_read_b128 v[168:171], v195 offset:18432
	ds_read_b128 v[172:175], v195 offset:19456
	ds_read_b128 v[182:185], v195 offset:20480
	ds_read_b128 v[186:189], v195 offset:21504
	ds_read_b128 v[196:199], v195 offset:22528
	ds_read_b128 v[200:203], v195 offset:23552
	global_load_lds_dwordx4 v152, s[62:63]
	v_lshl_add_u64 v[242:243], s[62:63], 0, v[148:149]
	s_mov_b32 m0, s28
	s_nop 0
	global_load_lds_dwordx4 v148, s[62:63]
	s_waitcnt vmcnt(10)
	s_setprio 1
	s_barrier
	s_waitcnt lgkmcnt(0)
	v_mfma_f32_16x16x32_bf16 v[60:63], v[80:83], v[160:163], v[60:63]
	v_mfma_f32_16x16x32_bf16 v[56:59], v[102:105], v[160:163], v[56:59]
	v_mfma_f32_16x16x32_bf16 v[44:47], v[80:83], v[168:171], v[44:47]
	v_mfma_f32_16x16x32_bf16 v[40:43], v[102:105], v[168:171], v[40:43]
	v_mfma_f32_16x16x32_bf16 v[28:31], v[80:83], v[182:185], v[28:31]
	v_mfma_f32_16x16x32_bf16 v[24:27], v[102:105], v[182:185], v[24:27]
	v_mfma_f32_16x16x32_bf16 v[12:15], v[80:83], v[196:199], v[12:15]
	v_mfma_f32_16x16x32_bf16 v[8:11], v[102:105], v[196:199], v[8:11]
	v_mfma_f32_16x16x32_bf16 v[60:63], v[88:91], v[164:167], v[60:63]
	v_mfma_f32_16x16x32_bf16 v[56:59], v[106:109], v[164:167], v[56:59]
	v_mfma_f32_16x16x32_bf16 v[44:47], v[88:91], v[172:175], v[44:47]
	v_mfma_f32_16x16x32_bf16 v[40:43], v[106:109], v[172:175], v[40:43]
	v_mfma_f32_16x16x32_bf16 v[28:31], v[88:91], v[186:189], v[28:31]
	v_mfma_f32_16x16x32_bf16 v[24:27], v[106:109], v[186:189], v[24:27]
	v_mfma_f32_16x16x32_bf16 v[12:15], v[88:91], v[200:203], v[12:15]
	v_mfma_f32_16x16x32_bf16 v[8:11], v[106:109], v[200:203], v[8:11]
	s_barrier
	s_setprio 0
	v_add_u32_e32 v96, 0x18000, v193
	ds_read_b128 v[80:83], v96
	ds_read_b128 v[88:91], v96 offset:1024
	ds_read_b128 v[102:105], v96 offset:2048
	ds_read_b128 v[106:109], v96 offset:3072
	s_add_u32 s74, s60, 0x40000
	s_addc_u32 s75, s61, 0
	s_add_i32 s72, s76, s18
	s_mov_b32 m0, s72
	s_nop 0
	global_load_lds_dwordx4 v150, s[74:75]
	s_add_i32 m0, s72, 0x2000
	s_nop 0
	global_load_lds_dwordx4 v146, s[74:75]
	s_waitcnt vmcnt(6)
	s_setprio 1
	s_barrier
	v_mfma_f32_16x16x32_bf16 v[52:55], v[224:227], v[160:163], v[52:55]
	v_mfma_f32_16x16x32_bf16 v[48:51], v[232:235], v[160:163], v[48:51]
	v_mfma_f32_16x16x32_bf16 v[36:39], v[224:227], v[168:171], v[36:39]
	s_add_i32 s72, 0, 0x18000
	v_mfma_f32_16x16x32_bf16 v[32:35], v[232:235], v[168:171], v[32:35]
	v_add_u32_e32 v96, s72, v193
	v_mfma_f32_16x16x32_bf16 v[20:23], v[224:227], v[182:185], v[20:23]
	v_mfma_f32_16x16x32_bf16 v[16:19], v[232:235], v[182:185], v[16:19]
	v_mfma_f32_16x16x32_bf16 v[4:7], v[224:227], v[196:199], v[4:7]
	v_mfma_f32_16x16x32_bf16 v[0:3], v[232:235], v[196:199], v[0:3]
	v_mfma_f32_16x16x32_bf16 v[52:55], v[228:231], v[164:167], v[52:55]
	v_mfma_f32_16x16x32_bf16 v[48:51], v[236:239], v[164:167], v[48:51]
	v_mfma_f32_16x16x32_bf16 v[36:39], v[228:231], v[172:175], v[36:39]
	v_mfma_f32_16x16x32_bf16 v[32:35], v[236:239], v[172:175], v[32:35]
	v_mfma_f32_16x16x32_bf16 v[20:23], v[228:231], v[186:189], v[20:23]
	v_mfma_f32_16x16x32_bf16 v[16:19], v[236:239], v[186:189], v[16:19]
	v_mfma_f32_16x16x32_bf16 v[4:7], v[228:231], v[200:203], v[4:7]
	v_mfma_f32_16x16x32_bf16 v[0:3], v[236:239], v[200:203], v[0:3]
	s_barrier
	s_setprio 0
	s_add_u32 s62, s62, 0x40000
	s_addc_u32 s63, s63, 0
	s_mov_b32 m0, s37
	ds_read_b128 v[160:163], v195 offset:32768
	ds_read_b128 v[164:167], v195 offset:33792
	ds_read_b128 v[168:171], v195 offset:34816
	ds_read_b128 v[172:175], v195 offset:35840
	ds_read_b128 v[182:185], v195 offset:36864
	ds_read_b128 v[186:189], v195 offset:37888
	ds_read_b128 v[196:199], v195 offset:38912
	ds_read_b128 v[200:203], v195 offset:39936
	global_load_lds_dwordx4 v152, s[62:63]
	s_mov_b32 m0, s56
	s_nop 0
	global_load_lds_dwordx4 v148, s[62:63]
	s_setprio 1
	s_barrier
	s_waitcnt lgkmcnt(0)
	v_mfma_f32_16x16x32_bf16 v[142:145], v[80:83], v[160:163], v[142:145]
	v_mfma_f32_16x16x32_bf16 v[138:141], v[102:105], v[160:163], v[138:141]
	v_mfma_f32_16x16x32_bf16 v[126:129], v[80:83], v[168:171], v[126:129]
	v_mfma_f32_16x16x32_bf16 v[122:125], v[102:105], v[168:171], v[122:125]
	v_mfma_f32_16x16x32_bf16 v[110:113], v[80:83], v[182:185], v[110:113]
	v_mfma_f32_16x16x32_bf16 v[98:101], v[102:105], v[182:185], v[98:101]
	v_mfma_f32_16x16x32_bf16 v[76:79], v[80:83], v[196:199], v[76:79]
	v_mfma_f32_16x16x32_bf16 v[72:75], v[102:105], v[196:199], v[72:75]
	v_mfma_f32_16x16x32_bf16 v[142:145], v[88:91], v[164:167], v[142:145]
	v_mfma_f32_16x16x32_bf16 v[138:141], v[106:109], v[164:167], v[138:141]
	v_mfma_f32_16x16x32_bf16 v[126:129], v[88:91], v[172:175], v[126:129]
	v_mfma_f32_16x16x32_bf16 v[122:125], v[106:109], v[172:175], v[122:125]
	v_mfma_f32_16x16x32_bf16 v[110:113], v[88:91], v[186:189], v[110:113]
	v_mfma_f32_16x16x32_bf16 v[98:101], v[106:109], v[186:189], v[98:101]
	v_mfma_f32_16x16x32_bf16 v[76:79], v[88:91], v[200:203], v[76:79]
	v_mfma_f32_16x16x32_bf16 v[72:75], v[106:109], v[200:203], v[72:75]
	s_barrier
	s_setprio 0
	s_add_i32 s62, 0, 0x1c000
	s_add_i32 s63, s72, s18
	v_add_u32_e32 v96, s62, v193
	v_lshl_add_u64 v[176:177], v[176:177], 0, s[6:7]
	s_mov_b32 m0, s63
	ds_read_b128 v[224:227], v96
	ds_read_b128 v[228:231], v96 offset:1024
	ds_read_b128 v[232:235], v96 offset:2048
	ds_read_b128 v[236:239], v96 offset:3072
	global_load_lds_dwordx4 v[176:177], off
	v_lshl_add_u64 v[176:177], v[190:191], 0, s[6:7]
	s_add_i32 m0, s63, 0x2000
	s_nop 0
	global_load_lds_dwordx4 v[176:177], off
	s_setprio 1
	s_barrier
	s_waitcnt lgkmcnt(0)
	v_mfma_f32_16x16x32_bf16 v[134:137], v[224:227], v[160:163], v[134:137]
	v_mfma_f32_16x16x32_bf16 v[130:133], v[232:235], v[160:163], v[130:133]
	v_mfma_f32_16x16x32_bf16 v[118:121], v[224:227], v[168:171], v[118:121]
	s_mov_b32 m0, s64
	v_mfma_f32_16x16x32_bf16 v[114:117], v[232:235], v[168:171], v[114:117]
	v_lshl_add_u64 v[176:177], v[240:241], 0, s[6:7]
	v_mfma_f32_16x16x32_bf16 v[92:95], v[224:227], v[182:185], v[92:95]
	v_mfma_f32_16x16x32_bf16 v[84:87], v[232:235], v[182:185], v[84:87]
	v_mfma_f32_16x16x32_bf16 v[68:71], v[224:227], v[196:199], v[68:71]
	v_mfma_f32_16x16x32_bf16 v[64:67], v[232:235], v[196:199], v[64:67]
	v_mfma_f32_16x16x32_bf16 v[134:137], v[228:231], v[164:167], v[134:137]
	v_mfma_f32_16x16x32_bf16 v[130:133], v[236:239], v[164:167], v[130:133]
	v_mfma_f32_16x16x32_bf16 v[118:121], v[228:231], v[172:175], v[118:121]
	v_mfma_f32_16x16x32_bf16 v[114:117], v[236:239], v[172:175], v[114:117]
	v_mfma_f32_16x16x32_bf16 v[92:95], v[228:231], v[186:189], v[92:95]
	v_mfma_f32_16x16x32_bf16 v[84:87], v[236:239], v[186:189], v[84:87]
	v_mfma_f32_16x16x32_bf16 v[68:71], v[228:231], v[200:203], v[68:71]
	v_mfma_f32_16x16x32_bf16 v[64:67], v[236:239], v[200:203], v[64:67]
	s_barrier
	s_setprio 0
	ds_read_b128 v[160:163], v195 offset:49152
	ds_read_b128 v[164:167], v195 offset:50176
	ds_read_b128 v[168:171], v195 offset:51200
	ds_read_b128 v[172:175], v195 offset:52224
	ds_read_b128 v[182:185], v195 offset:53248
	ds_read_b128 v[186:189], v195 offset:54272
	ds_read_b128 v[196:199], v195 offset:55296
	ds_read_b128 v[200:203], v195 offset:56320
	global_load_lds_dwordx4 v[176:177], off
	v_lshl_add_u64 v[176:177], v[242:243], 0, s[6:7]
	s_mov_b32 m0, s65
	s_nop 0
	global_load_lds_dwordx4 v[176:177], off
	s_waitcnt vmcnt(10)
	s_setprio 1
	s_barrier
	s_waitcnt lgkmcnt(0)
	v_mfma_f32_16x16x32_bf16 v[60:63], v[80:83], v[160:163], v[60:63]
	v_mfma_f32_16x16x32_bf16 v[56:59], v[102:105], v[160:163], v[56:59]
	v_mfma_f32_16x16x32_bf16 v[44:47], v[80:83], v[168:171], v[44:47]
	v_mfma_f32_16x16x32_bf16 v[40:43], v[102:105], v[168:171], v[40:43]
	v_mfma_f32_16x16x32_bf16 v[28:31], v[80:83], v[182:185], v[28:31]
	v_mfma_f32_16x16x32_bf16 v[24:27], v[102:105], v[182:185], v[24:27]
	v_mfma_f32_16x16x32_bf16 v[12:15], v[80:83], v[196:199], v[12:15]
	v_mfma_f32_16x16x32_bf16 v[8:11], v[102:105], v[196:199], v[8:11]
	v_mfma_f32_16x16x32_bf16 v[60:63], v[88:91], v[164:167], v[60:63]
	v_mfma_f32_16x16x32_bf16 v[56:59], v[106:109], v[164:167], v[56:59]
	v_mfma_f32_16x16x32_bf16 v[44:47], v[88:91], v[172:175], v[44:47]
	v_mfma_f32_16x16x32_bf16 v[40:43], v[106:109], v[172:175], v[40:43]
	v_mfma_f32_16x16x32_bf16 v[28:31], v[88:91], v[186:189], v[28:31]
	v_mfma_f32_16x16x32_bf16 v[24:27], v[106:109], v[186:189], v[24:27]
	v_mfma_f32_16x16x32_bf16 v[12:15], v[88:91], v[200:203], v[12:15]
	v_mfma_f32_16x16x32_bf16 v[8:11], v[106:109], v[200:203], v[8:11]
	s_barrier
	s_setprio 0
	v_add_u32_e32 v96, 0x10000, v193
	ds_read_b128 v[80:83], v96
	ds_read_b128 v[88:91], v96 offset:1024
	ds_read_b128 v[102:105], v96 offset:2048
	ds_read_b128 v[106:109], v96 offset:3072
	s_add_u32 s60, s60, 0x40080
	s_addc_u32 s61, s61, 0
	s_add_i32 s62, s62, s18
	s_mov_b32 m0, s62
	s_nop 0
	global_load_lds_dwordx4 v150, s[60:61]
	s_add_i32 m0, s62, 0x2000
	s_nop 0
	global_load_lds_dwordx4 v146, s[60:61]
	s_waitcnt vmcnt(6)
	s_setprio 1
	s_barrier
	v_mfma_f32_16x16x32_bf16 v[52:55], v[224:227], v[160:163], v[52:55]
	v_mfma_f32_16x16x32_bf16 v[48:51], v[232:235], v[160:163], v[48:51]
	v_mfma_f32_16x16x32_bf16 v[36:39], v[224:227], v[168:171], v[36:39]
	s_add_i32 s71, s71, 2
	v_mfma_f32_16x16x32_bf16 v[32:35], v[232:235], v[168:171], v[32:35]
	s_add_u32 s58, s58, 0x100
	v_mfma_f32_16x16x32_bf16 v[20:23], v[224:227], v[182:185], v[20:23]
	s_addc_u32 s59, s59, 0
	v_mfma_f32_16x16x32_bf16 v[16:19], v[232:235], v[182:185], v[16:19]
	s_add_u32 s69, s69, 0x100
	v_mfma_f32_16x16x32_bf16 v[4:7], v[224:227], v[196:199], v[4:7]
	s_addc_u32 s70, s70, 0
	v_mfma_f32_16x16x32_bf16 v[0:3], v[232:235], v[196:199], v[0:3]
	s_cmp_gt_u32 s71, 13
	v_mfma_f32_16x16x32_bf16 v[52:55], v[228:231], v[164:167], v[52:55]
	v_mfma_f32_16x16x32_bf16 v[48:51], v[236:239], v[164:167], v[48:51]
	v_mfma_f32_16x16x32_bf16 v[36:39], v[228:231], v[172:175], v[36:39]
	v_mfma_f32_16x16x32_bf16 v[32:35], v[236:239], v[172:175], v[32:35]
	v_mfma_f32_16x16x32_bf16 v[20:23], v[228:231], v[186:189], v[20:23]
	v_mfma_f32_16x16x32_bf16 v[16:19], v[236:239], v[186:189], v[16:19]
	v_mfma_f32_16x16x32_bf16 v[4:7], v[228:231], v[200:203], v[4:7]
	v_mfma_f32_16x16x32_bf16 v[0:3], v[236:239], v[200:203], v[0:3]
	s_barrier
	s_setprio 0
	s_cbranch_scc0 .LBB0_557
	s_waitcnt lgkmcnt(0)
	s_lshl_b32 s47, s54, 8
	s_add_i32 s47, s47, s57
	v_or_b32_e32 v162, s47, v192
	s_lshl_b32 s100, s57, 2
	s_add_i32 s100, s100, 0x20000
	v_lshl_add_u32 v244, v192, 2, s100
	ds_read_b32 v245, v244 offset:64
	ds_read_b32 v246, v244 offset:128
	ds_read_b32 v247, v244 offset:192
	ds_read_b32 v248, v244 offset:512
	ds_read_b32 v249, v244 offset:576
	ds_read_b32 v250, v244 offset:640
	ds_read_b32 v251, v244 offset:704
	ds_read_b32 v244, v244
	v_or_b32_e32 v190, 16, v162
	v_or_b32_e32 v188, 32, v162
	v_or_b32_e32 v186, 48, v162
	v_add_u32_e32 v184, 0x80, v162
	v_add_u32_e32 v172, 0x90, v162
	v_add_u32_e32 v168, 0xa0, v162
	v_add_u32_e32 v164, 0xb0, v162
	s_cmpk_lt_u32 s47, 0x2000
	s_cselect_b32 s47, 1, 2
	v_mov_b32_e32 v218, s47
	v_cmp_lt_i32_e32 vcc, s23, v162
	v_lshl_or_b32 v166, s55, 8, v194
	v_ashrrev_i32_e32 v167, 31, v166
	v_cndmask_b32_e32 v185, 0, v218, vcc
	v_mul_u32_u24_e32 v82, 0x7600, v185
	v_lshlrev_b32_e32 v96, 2, v82
	v_lshl_add_u64 v[80:81], s[44:45], 0, v[96:97]
	v_lshl_add_u64 v[106:107], v[166:167], 2, v[80:81]
	global_load_dwordx4 v[80:83], v[106:107], off offset:16
	global_load_dwordx4 v[88:91], v[106:107], off
	global_load_dwordx4 v[102:105], v[106:107], off offset:528
	s_nop 0
	global_load_dwordx4 v[106:109], v[106:107], off offset:512
	v_lshl_or_b32 v160, s55, 7, v194
	v_cmp_lt_i32_e32 vcc, s23, v190
	s_waitcnt vmcnt(0)
	s_waitcnt lgkmcnt(0)
	v_add_f32_e32 v96, v244, v244
	v_mov_b32_e32 v201, v245
	v_mov_b32_e32 v199, v246
	v_mov_b32_e32 v197, v247
	v_mov_b32_e32 v191, v248
	v_mov_b32_e32 v187, v249
	v_mov_b32_e32 v169, v250
	v_mov_b32_e32 v163, v251
	v_fmamk_f32 v96, v96, 0x3a800000, v207
	v_rsq_f32_e32 v96, v96
	v_mov_b64_e32 v[170:171], s[42:43]
	v_ashrrev_i32_e32 v161, 31, v160
	v_mad_i64_i32 v[170:171], s[54:55], v162, s31, v[170:171]
	v_lshl_add_u64 v[224:225], v[160:161], 1, v[170:171]
	v_pk_mul_f32 v[182:183], v[82:83], s[0:1] op_sel_hi:[1,0]
	v_pk_mul_f32 v[176:177], v[80:81], s[0:1] op_sel_hi:[1,0]
	v_pk_mul_f32 v[174:175], v[90:91], s[0:1] op_sel_hi:[1,0]
	v_pk_mul_f32 v[170:171], v[88:89], s[0:1] op_sel_hi:[1,0]
	v_mul_f32_e32 v226, 0xbfb8aa3b, v96
	v_pk_fma_f32 v[228:229], v[144:145], v[226:227], v[174:175] op_sel_hi:[1,0,1]
	v_pk_fma_f32 v[230:231], v[142:143], v[226:227], v[170:171] op_sel_hi:[1,0,1]
	v_pk_fma_f32 v[232:233], v[140:141], v[226:227], v[182:183] op_sel_hi:[1,0,1]
	v_pk_fma_f32 v[226:227], v[138:139], v[226:227], v[176:177] op_sel_hi:[1,0,1]
	v_exp_f32_e32 v230, v230
	v_exp_f32_e32 v226, v226
	v_exp_f32_e32 v231, v231
	v_exp_f32_e32 v227, v227
	v_exp_f32_e32 v232, v232
	v_exp_f32_e32 v233, v233
	v_exp_f32_e32 v228, v228
	v_exp_f32_e32 v229, v229
	v_pk_add_f32 v[230:231], v[230:231], 1.0 op_sel_hi:[1,0]
	v_pk_add_f32 v[232:233], v[232:233], 1.0 op_sel_hi:[1,0]
	v_pk_add_f32 v[226:227], v[226:227], 1.0 op_sel_hi:[1,0]
	v_pk_add_f32 v[228:229], v[228:229], 1.0 op_sel_hi:[1,0]
	v_rcp_f32_e32 v230, v230
	v_rcp_f32_e32 v226, v226
	v_rcp_f32_e32 v231, v231
	v_rcp_f32_e32 v227, v227
	v_rcp_f32_e32 v232, v232
	v_rcp_f32_e32 v233, v233
	v_rcp_f32_e32 v228, v228
	v_rcp_f32_e32 v229, v229
	v_pk_fma_f32 v[142:143], v[142:143], v[96:97], v[88:89] op_sel_hi:[1,0,1]
	v_pk_fma_f32 v[140:141], v[140:141], v[96:97], v[82:83] op_sel_hi:[1,0,1]
	v_pk_fma_f32 v[138:139], v[138:139], v[96:97], v[80:81] op_sel_hi:[1,0,1]
	v_pk_fma_f32 v[134:135], v[134:135], v[96:97], v[106:107] op_sel_hi:[1,0,1]
	v_pk_fma_f32 v[132:133], v[132:133], v[96:97], v[104:105] op_sel_hi:[1,0,1]
	v_pk_fma_f32 v[130:131], v[130:131], v[96:97], v[102:103] op_sel_hi:[1,0,1]
	v_pk_fma_f32 v[144:145], v[144:145], v[96:97], v[90:91] op_sel_hi:[1,0,1]
	v_pk_fma_f32 v[136:137], v[136:137], v[96:97], v[108:109] op_sel_hi:[1,0,1]
	v_pk_mul_f32 v[134:135], v[142:143], v[134:135]
	v_pk_mul_f32 v[132:133], v[140:141], v[132:133]
	v_pk_mul_f32 v[130:131], v[138:139], v[130:131]
	v_pk_mul_f32 v[136:137], v[144:145], v[136:137]
	v_pk_mul_f32 v[134:135], v[134:135], v[230:231]
	v_pk_mul_f32 v[138:139], v[132:133], v[232:233]
	v_pk_mul_f32 v[132:133], v[130:131], v[226:227]
	v_cvt_pk_bf16_f32 v130, v134, v135
	v_mov_b32_e32 v202, v201
	v_mov_b32_e32 v200, v199
	v_mov_b32_e32 v198, v197
	v_mov_b32_e32 v196, v191
	v_mov_b32_e32 v189, v187
	v_mov_b32_e32 v173, v169
	v_mov_b32_e32 v165, v163
	v_pk_mul_f32 v[136:137], v[136:137], v[228:229]
	v_permlane32_swap_b32_e32 v201, v202
	v_cvt_pk_bf16_f32 v131, v136, v137
	v_cvt_pk_bf16_f32 v132, v132, v133
	v_cvt_pk_bf16_f32 v133, v138, v139
	global_store_dwordx4 v[224:225], v[130:133], off
	v_permlane32_swap_b32_e32 v199, v200
	s_nop 0
	v_cndmask_b32_e32 v130, 0, v218, vcc
	v_permlane32_swap_b32_e32 v197, v198
	v_permlane32_swap_b32_e32 v191, v196
	v_permlane32_swap_b32_e32 v187, v189
	v_permlane32_swap_b32_e32 v169, v173
	v_permlane32_swap_b32_e32 v163, v165
	v_cmp_ne_u32_e32 vcc, v130, v185
	s_and_saveexec_b64 s[54:55], vcc
	s_cbranch_execz .LBB0_560
	v_mul_u32_u24_e32 v80, 0x7600, v130
	v_lshlrev_b32_e32 v96, 2, v80
	v_lshl_add_u64 v[80:81], s[44:45], 0, v[96:97]
	v_lshl_add_u64 v[106:107], v[166:167], 2, v[80:81]
	global_load_dwordx4 v[88:91], v[106:107], off
	global_load_dwordx4 v[80:83], v[106:107], off offset:16
	global_load_dwordx4 v[102:105], v[106:107], off offset:528
	s_nop 0
	global_load_dwordx4 v[106:109], v[106:107], off offset:512
	v_mov_b32_e32 v185, v130
	s_waitcnt vmcnt(0)
	v_pk_mul_f32 v[170:171], v[88:89], s[0:1] op_sel_hi:[1,0]
	v_pk_mul_f32 v[174:175], v[90:91], s[0:1] op_sel_hi:[1,0]
	v_pk_mul_f32 v[176:177], v[80:81], s[0:1] op_sel_hi:[1,0]
	v_pk_mul_f32 v[182:183], v[82:83], s[0:1] op_sel_hi:[1,0]
